# v59 + hg_pass3 unit front end: S tile and both Q0 slices loaded in one round trip
# baseline (speedup 1.0000x reference)
; __device__ __forceinline__ unsigned pk2(float lo, float hi) { return cvt_pk_bf16(lo, hi); }
; #define UT2(p) ({ const unsigned w_ = *(const unsigned*)(p); (f32x2){__uint_as_float(w_ << 16), __uint_as_float(w_ & 0xffff0000u)}; })
; __device__ __forceinline__ void hg_pass2(Frame& F) {
;     ...
;     for (int e = gt; e < 8 * 16 * 128 * 64; e += NT) { const int dp = e & 63, v = (e >> 6) & 127, sh = e >> 13, d = 2 * dp;
;         const size_t u = 4096 + sh; const size_t so = ((size_t)sh * 128 + d) * 128 + v;
;         const f32x2 S = (f32x2){S0[so], S0[so + 128]};
;         const f32x2 a = *(const f32x2*)(ADEC + u * 128 + d), ut = UT2(UT + (u * 128 + v) * 128 + d);
;         *(unsigned*)(ST + (u * 128 + v) * 128 + d) = pk2(S[0], S[1]);
;         const f32x2 Sn = a * S + ut;
;         float* o = F.out + O_HGS + so; o[0] = Sn[0]; o[128] = Sn[1]; }
.LBB0_740:
	s_waitcnt vmcnt(3) lgkmcnt(0)
	v_ashrrev_i32_e32 v4, 13, v168
	v_and_b32_e32 v14, 0x7e, v1
	v_add_u32_e32 v6, 0x1000, v4
	v_ashrrev_i32_e32 v5, 31, v4
	v_bfe_u32 v10, v168, 6, 7
	v_lshlrev_b32_e32 v8, 7, v14
	v_ashrrev_i32_e32 v7, 31, v6
	v_lshlrev_b64 v[4:5], 14, v[4:5]
	v_or3_b32 v4, v4, v8, v10
	v_lshlrev_b64 v[8:9], 9, v[6:7]
	v_lshlrev_b64 v[6:7], 15, v[6:7]
	v_lshlrev_b32_e32 v2, 2, v14
	v_lshl_add_u64 v[8:9], s[10:11], 0, v[8:9]
	v_lshl_or_b32 v6, v10, 8, v6
	v_lshlrev_b64 v[4:5], 2, v[4:5]
	v_lshl_add_u64 v[8:9], v[8:9], 0, v[2:3]
	v_lshl_add_u64 v[12:13], s[0:1], 0, v[6:7]
	v_lshlrev_b32_e32 v2, 1, v14
	v_lshl_add_u64 v[10:11], s[8:9], 0, v[4:5]
	v_lshl_add_u64 v[12:13], v[12:13], 0, v[2:3]
	global_load_dword v90, v[10:11], off
	global_load_dwordx2 v[84:85], v[8:9], off
	global_load_dword v92, v[12:13], off
	global_load_dword v91, v[10:11], off offset:512
	v_add_u32_e32 v168, s49, v168
	v_lshl_add_u64 v[6:7], s[4:5], 0, v[6:7]
	v_lshl_add_u64 v[86:87], v[6:7], 0, v[2:3]
	v_add_u32_e32 v1, s3, v1
	v_lshl_add_u64 v[88:89], s[12:13], 0, v[4:5]
	v_ashrrev_i32_e32 v4, 13, v168
	v_and_b32_e32 v14, 0x7e, v1
	v_add_u32_e32 v6, 0x1000, v4
	v_ashrrev_i32_e32 v5, 31, v4
	v_bfe_u32 v10, v168, 6, 7
	v_lshlrev_b32_e32 v8, 7, v14
	v_ashrrev_i32_e32 v7, 31, v6
	v_lshlrev_b64 v[4:5], 14, v[4:5]
	v_or3_b32 v4, v4, v8, v10
	v_lshlrev_b64 v[8:9], 9, v[6:7]
	v_lshlrev_b64 v[6:7], 15, v[6:7]
	v_lshlrev_b32_e32 v2, 2, v14
	v_lshl_add_u64 v[8:9], s[10:11], 0, v[8:9]
	v_lshl_or_b32 v6, v10, 8, v6
	v_lshlrev_b64 v[4:5], 2, v[4:5]
	v_lshl_add_u64 v[8:9], v[8:9], 0, v[2:3]
	v_lshl_add_u64 v[12:13], s[0:1], 0, v[6:7]
	v_lshlrev_b32_e32 v2, 1, v14
	v_lshl_add_u64 v[10:11], s[8:9], 0, v[4:5]
	v_lshl_add_u64 v[12:13], v[12:13], 0, v[2:3]
	global_load_dword v100, v[10:11], off
	global_load_dwordx2 v[94:95], v[8:9], off
	global_load_dword v102, v[12:13], off
	global_load_dword v101, v[10:11], off offset:512
	v_add_u32_e32 v168, s49, v168
	v_lshl_add_u64 v[6:7], s[4:5], 0, v[6:7]
	v_lshl_add_u64 v[96:97], v[6:7], 0, v[2:3]
	v_add_u32_e32 v1, s3, v1
	v_lshl_add_u64 v[98:99], s[12:13], 0, v[4:5]
	v_ashrrev_i32_e32 v4, 13, v168
	v_and_b32_e32 v14, 0x7e, v1
	v_add_u32_e32 v6, 0x1000, v4
	v_ashrrev_i32_e32 v5, 31, v4
	v_bfe_u32 v10, v168, 6, 7
	v_lshlrev_b32_e32 v8, 7, v14
	v_ashrrev_i32_e32 v7, 31, v6
	v_lshlrev_b64 v[4:5], 14, v[4:5]
	v_or3_b32 v4, v4, v8, v10
	v_lshlrev_b64 v[8:9], 9, v[6:7]
	v_lshlrev_b64 v[6:7], 15, v[6:7]
	v_lshlrev_b32_e32 v2, 2, v14
	v_lshl_add_u64 v[8:9], s[10:11], 0, v[8:9]
	v_lshl_or_b32 v6, v10, 8, v6
	v_lshlrev_b64 v[4:5], 2, v[4:5]
	v_lshl_add_u64 v[8:9], v[8:9], 0, v[2:3]
	v_lshl_add_u64 v[12:13], s[0:1], 0, v[6:7]
	v_lshlrev_b32_e32 v2, 1, v14
	v_lshl_add_u64 v[10:11], s[8:9], 0, v[4:5]
	v_lshl_add_u64 v[12:13], v[12:13], 0, v[2:3]
	global_load_dword v110, v[10:11], off
	global_load_dwordx2 v[104:105], v[8:9], off
	global_load_dword v112, v[12:13], off
	global_load_dword v111, v[10:11], off offset:512
	v_add_u32_e32 v168, s49, v168
	v_lshl_add_u64 v[6:7], s[4:5], 0, v[6:7]
	v_lshl_add_u64 v[106:107], v[6:7], 0, v[2:3]
	v_add_u32_e32 v1, s3, v1
	v_lshl_add_u64 v[108:109], s[12:13], 0, v[4:5]
	v_ashrrev_i32_e32 v4, 13, v168
	v_and_b32_e32 v14, 0x7e, v1
	v_add_u32_e32 v6, 0x1000, v4
	v_ashrrev_i32_e32 v5, 31, v4
	v_bfe_u32 v10, v168, 6, 7
	v_lshlrev_b32_e32 v8, 7, v14
	v_ashrrev_i32_e32 v7, 31, v6
	v_lshlrev_b64 v[4:5], 14, v[4:5]
	v_or3_b32 v4, v4, v8, v10
	v_lshlrev_b64 v[8:9], 9, v[6:7]
	v_lshlrev_b64 v[6:7], 15, v[6:7]
	v_lshlrev_b32_e32 v2, 2, v14
	v_lshl_add_u64 v[8:9], s[10:11], 0, v[8:9]
	v_lshl_or_b32 v6, v10, 8, v6
	v_lshlrev_b64 v[4:5], 2, v[4:5]
	v_lshl_add_u64 v[8:9], v[8:9], 0, v[2:3]
	v_lshl_add_u64 v[12:13], s[0:1], 0, v[6:7]
	v_lshlrev_b32_e32 v2, 1, v14
	v_lshl_add_u64 v[10:11], s[8:9], 0, v[4:5]
	v_lshl_add_u64 v[12:13], v[12:13], 0, v[2:3]
	global_load_dword v120, v[10:11], off
	global_load_dwordx2 v[114:115], v[8:9], off
	global_load_dword v122, v[12:13], off
	global_load_dword v121, v[10:11], off offset:512
	v_add_u32_e32 v168, s49, v168
	v_lshl_add_u64 v[6:7], s[4:5], 0, v[6:7]
	v_lshl_add_u64 v[116:117], v[6:7], 0, v[2:3]
	v_add_u32_e32 v1, s3, v1
	v_lshl_add_u64 v[118:119], s[12:13], 0, v[4:5]
	v_ashrrev_i32_e32 v4, 13, v168
	v_and_b32_e32 v14, 0x7e, v1
	v_add_u32_e32 v6, 0x1000, v4
	v_ashrrev_i32_e32 v5, 31, v4
	v_bfe_u32 v10, v168, 6, 7
	v_lshlrev_b32_e32 v8, 7, v14
	v_ashrrev_i32_e32 v7, 31, v6
	v_lshlrev_b64 v[4:5], 14, v[4:5]
	v_or3_b32 v4, v4, v8, v10
	v_lshlrev_b64 v[8:9], 9, v[6:7]
	v_lshlrev_b64 v[6:7], 15, v[6:7]
	v_lshlrev_b32_e32 v2, 2, v14
	v_lshl_add_u64 v[8:9], s[10:11], 0, v[8:9]
	v_lshl_or_b32 v6, v10, 8, v6
	v_lshlrev_b64 v[4:5], 2, v[4:5]
	v_lshl_add_u64 v[8:9], v[8:9], 0, v[2:3]
	v_lshl_add_u64 v[12:13], s[0:1], 0, v[6:7]
	v_lshlrev_b32_e32 v2, 1, v14
	v_lshl_add_u64 v[10:11], s[8:9], 0, v[4:5]
	v_lshl_add_u64 v[12:13], v[12:13], 0, v[2:3]
	global_load_dword v130, v[10:11], off
	global_load_dwordx2 v[124:125], v[8:9], off
	global_load_dword v132, v[12:13], off
	global_load_dword v131, v[10:11], off offset:512
	v_add_u32_e32 v168, s49, v168
	v_lshl_add_u64 v[6:7], s[4:5], 0, v[6:7]
	v_lshl_add_u64 v[126:127], v[6:7], 0, v[2:3]
	v_add_u32_e32 v1, s3, v1
	v_lshl_add_u64 v[128:129], s[12:13], 0, v[4:5]
	v_ashrrev_i32_e32 v4, 13, v168
	v_and_b32_e32 v14, 0x7e, v1
	v_add_u32_e32 v6, 0x1000, v4
	v_ashrrev_i32_e32 v5, 31, v4
	v_bfe_u32 v10, v168, 6, 7
	v_lshlrev_b32_e32 v8, 7, v14
; __device__ __forceinline__ unsigned pk2(float lo, float hi) { return cvt_pk_bf16(lo, hi); }
; #define UT2(p) ({ const unsigned w_ = *(const unsigned*)(p); (f32x2){__uint_as_float(w_ << 16), __uint_as_float(w_ & 0xffff0000u)}; })
; __device__ __forceinline__ void hg_pass2(Frame& F) {
;     ...
;     for (int e = gt; e < 8 * 16 * 128 * 64; e += NT) { const int dp = e & 63, v = (e >> 6) & 127, sh = e >> 13, d = 2 * dp;
;         const size_t u = 4096 + sh; const size_t so = ((size_t)sh * 128 + d) * 128 + v;
;         const f32x2 S = (f32x2){S0[so], S0[so + 128]};
;         const f32x2 a = *(const f32x2*)(ADEC + u * 128 + d), ut = UT2(UT + (u * 128 + v) * 128 + d);
;         *(unsigned*)(ST + (u * 128 + v) * 128 + d) = pk2(S[0], S[1]);
;         const f32x2 Sn = a * S + ut;
;         float* o = F.out + O_HGS + so; o[0] = Sn[0]; o[128] = Sn[1]; }
	v_ashrrev_i32_e32 v7, 31, v6
	v_lshlrev_b64 v[4:5], 14, v[4:5]
	v_or3_b32 v4, v4, v8, v10
	v_lshlrev_b64 v[8:9], 9, v[6:7]
	v_lshlrev_b64 v[6:7], 15, v[6:7]
	v_lshlrev_b32_e32 v2, 2, v14
	v_lshl_add_u64 v[8:9], s[10:11], 0, v[8:9]
	v_lshl_or_b32 v6, v10, 8, v6
	v_lshlrev_b64 v[4:5], 2, v[4:5]
	v_lshl_add_u64 v[8:9], v[8:9], 0, v[2:3]
	v_lshl_add_u64 v[12:13], s[0:1], 0, v[6:7]
	v_lshlrev_b32_e32 v2, 1, v14
	v_lshl_add_u64 v[10:11], s[8:9], 0, v[4:5]
	v_lshl_add_u64 v[12:13], v[12:13], 0, v[2:3]
	global_load_dword v140, v[10:11], off
	global_load_dwordx2 v[134:135], v[8:9], off
	global_load_dword v142, v[12:13], off
	global_load_dword v141, v[10:11], off offset:512
	v_add_u32_e32 v168, s49, v168
	v_lshl_add_u64 v[6:7], s[4:5], 0, v[6:7]
	v_lshl_add_u64 v[136:137], v[6:7], 0, v[2:3]
	v_add_u32_e32 v1, s3, v1
	v_lshl_add_u64 v[138:139], s[12:13], 0, v[4:5]
	v_ashrrev_i32_e32 v4, 13, v168
	v_and_b32_e32 v14, 0x7e, v1
	v_add_u32_e32 v6, 0x1000, v4
	v_ashrrev_i32_e32 v5, 31, v4
	v_bfe_u32 v10, v168, 6, 7
	v_lshlrev_b32_e32 v8, 7, v14
	v_ashrrev_i32_e32 v7, 31, v6
	v_lshlrev_b64 v[4:5], 14, v[4:5]
	v_or3_b32 v4, v4, v8, v10
	v_lshlrev_b64 v[8:9], 9, v[6:7]
	v_lshlrev_b64 v[6:7], 15, v[6:7]
	v_lshlrev_b32_e32 v2, 2, v14
	v_lshl_add_u64 v[8:9], s[10:11], 0, v[8:9]
	v_lshl_or_b32 v6, v10, 8, v6
	v_lshlrev_b64 v[4:5], 2, v[4:5]
	v_lshl_add_u64 v[8:9], v[8:9], 0, v[2:3]
	v_lshl_add_u64 v[12:13], s[0:1], 0, v[6:7]
	v_lshlrev_b32_e32 v2, 1, v14
	v_lshl_add_u64 v[10:11], s[8:9], 0, v[4:5]
	v_lshl_add_u64 v[12:13], v[12:13], 0, v[2:3]
	global_load_dword v210, v[10:11], off
	global_load_dwordx2 v[204:205], v[8:9], off
	global_load_dword v212, v[12:13], off
	global_load_dword v211, v[10:11], off offset:512
	v_add_u32_e32 v168, s49, v168
	v_lshl_add_u64 v[6:7], s[4:5], 0, v[6:7]
	v_lshl_add_u64 v[206:207], v[6:7], 0, v[2:3]
	v_add_u32_e32 v1, s3, v1
	v_lshl_add_u64 v[208:209], s[12:13], 0, v[4:5]
	v_ashrrev_i32_e32 v4, 13, v168
	v_and_b32_e32 v14, 0x7e, v1
	v_add_u32_e32 v6, 0x1000, v4
	v_ashrrev_i32_e32 v5, 31, v4
	v_bfe_u32 v10, v168, 6, 7
	v_lshlrev_b32_e32 v8, 7, v14
	v_ashrrev_i32_e32 v7, 31, v6
	v_lshlrev_b64 v[4:5], 14, v[4:5]
	v_or3_b32 v4, v4, v8, v10
	v_lshlrev_b64 v[8:9], 9, v[6:7]
	v_lshlrev_b64 v[6:7], 15, v[6:7]
	v_lshlrev_b32_e32 v2, 2, v14
	v_lshl_add_u64 v[8:9], s[10:11], 0, v[8:9]
	v_lshl_or_b32 v6, v10, 8, v6
	v_lshlrev_b64 v[4:5], 2, v[4:5]
	v_lshl_add_u64 v[8:9], v[8:9], 0, v[2:3]
	v_lshl_add_u64 v[12:13], s[0:1], 0, v[6:7]
	v_lshlrev_b32_e32 v2, 1, v14
	v_lshl_add_u64 v[10:11], s[8:9], 0, v[4:5]
	v_lshl_add_u64 v[12:13], v[12:13], 0, v[2:3]
	global_load_dword v220, v[10:11], off
	global_load_dwordx2 v[214:215], v[8:9], off
	global_load_dword v222, v[12:13], off
	global_load_dword v221, v[10:11], off offset:512
	v_add_u32_e32 v168, s49, v168
	v_lshl_add_u64 v[6:7], s[4:5], 0, v[6:7]
	v_lshl_add_u64 v[216:217], v[6:7], 0, v[2:3]
	v_add_u32_e32 v1, s3, v1
	v_lshl_add_u64 v[218:219], s[12:13], 0, v[4:5]
	s_waitcnt vmcnt(28)
	v_lshlrev_b32_e32 v10, 16, v92
	v_cvt_pk_bf16_f32 v2, v90, v91
	v_and_b32_e32 v11, 0xffff0000, v92
	global_store_dword v[86:87], v2, off
	v_pk_fma_f32 v[6:7], v[84:85], v[90:91], v[10:11]
	global_store_dword v[88:89], v6, off
	global_store_dword v[88:89], v7, off offset:512
	s_waitcnt vmcnt(27)
	v_lshlrev_b32_e32 v10, 16, v102
	v_cvt_pk_bf16_f32 v2, v100, v101
	v_and_b32_e32 v11, 0xffff0000, v102
	global_store_dword v[96:97], v2, off
	v_pk_fma_f32 v[6:7], v[94:95], v[100:101], v[10:11]
	global_store_dword v[98:99], v6, off
	global_store_dword v[98:99], v7, off offset:512
	s_waitcnt vmcnt(26)
	v_lshlrev_b32_e32 v10, 16, v112
	v_cvt_pk_bf16_f32 v2, v110, v111
	v_and_b32_e32 v11, 0xffff0000, v112
	global_store_dword v[106:107], v2, off
	v_pk_fma_f32 v[6:7], v[104:105], v[110:111], v[10:11]
	global_store_dword v[108:109], v6, off
	global_store_dword v[108:109], v7, off offset:512
	s_waitcnt vmcnt(25)
	v_lshlrev_b32_e32 v10, 16, v122
	v_cvt_pk_bf16_f32 v2, v120, v121
	v_and_b32_e32 v11, 0xffff0000, v122
	global_store_dword v[116:117], v2, off
	v_pk_fma_f32 v[6:7], v[114:115], v[120:121], v[10:11]
	global_store_dword v[118:119], v6, off
	global_store_dword v[118:119], v7, off offset:512
	s_waitcnt vmcnt(24)
	v_lshlrev_b32_e32 v10, 16, v132
	v_cvt_pk_bf16_f32 v2, v130, v131
	v_and_b32_e32 v11, 0xffff0000, v132
	global_store_dword v[126:127], v2, off
	v_pk_fma_f32 v[6:7], v[124:125], v[130:131], v[10:11]
	global_store_dword v[128:129], v6, off
	global_store_dword v[128:129], v7, off offset:512
	s_waitcnt vmcnt(23)
	v_lshlrev_b32_e32 v10, 16, v142
	v_cvt_pk_bf16_f32 v2, v140, v141
	v_and_b32_e32 v11, 0xffff0000, v142
	global_store_dword v[136:137], v2, off
	v_pk_fma_f32 v[6:7], v[134:135], v[140:141], v[10:11]
	global_store_dword v[138:139], v6, off
	global_store_dword v[138:139], v7, off offset:512
	s_waitcnt vmcnt(22)
	v_lshlrev_b32_e32 v10, 16, v212
	v_cvt_pk_bf16_f32 v2, v210, v211
	v_and_b32_e32 v11, 0xffff0000, v212
	global_store_dword v[206:207], v2, off
	v_pk_fma_f32 v[6:7], v[204:205], v[210:211], v[10:11]
	global_store_dword v[208:209], v6, off
	global_store_dword v[208:209], v7, off offset:512
	s_waitcnt vmcnt(21)
	v_lshlrev_b32_e32 v10, 16, v222
	v_cvt_pk_bf16_f32 v2, v220, v221
	v_and_b32_e32 v11, 0xffff0000, v222
	global_store_dword v[216:217], v2, off
	v_pk_fma_f32 v[6:7], v[214:215], v[220:221], v[10:11]
	global_store_dword v[218:219], v6, off
	global_store_dword v[218:219], v7, off offset:512

; #define LAS __attribute__((address_space(3)))
; #define MFMA32(a, b, c) __builtin_amdgcn_mfma_f32_32x32x16_bf16((a), (b), (c), 0, 0, 0)
; __device__ __forceinline__ void hg_pass3(Frame& F) {
;     ...
;         int h, row0, nvalid; hg_decode(u, h, row0, nvalid);
; #pragma unroll
;         for (int i = 0; i < 4; ++i) { const int c = tid + 512 * i, v = c >> 4, d8 = (c & 15) * 8;
;             *(LAS u32x4*)(STl + v * 136 + d8) = *(const u32x4*)(ST + ((size_t)u * 128 + v) * 128 + d8); }
; #pragma unroll
;         for (int i = 0; i < 2; ++i) { const int c = tid + 512 * i, t = c >> 4, d8 = (c & 15) * 8;
;             u32x4 x = (u32x4){0u, 0u, 0u, 0u}; if (t < nvalid) x = *(const u32x4*)(Q0 + (size_t)(row0 + t) * DH + h * 128 + d8);
;             *(LAS u32x4*)(Q0l + t * 136 + d8) = x; }
;         const int tv = w >> 1, tt = w & 1, t = 32 * tt + r; const bool tvalid = t < nvalid;
;         const size_t rowg = (size_t)(row0 + (tvalid ? t : 0));
;         const int vb = h * 128 + 32 * tv + 4 * hh;
;         f32x4 oi[4]; u32x2 gwv[4];
; #pragma unroll
;         for (int g = 0; g < 4; ++g) { const u32x2 ow = *(const u32x2*)(OI + rowg * DH + vb + 8 * g); oi[g] = (f32x4){__uint_as_float(ow.x << 16), __uint_as_float(ow.x & 0xffff0000u), __uint_as_float(ow.y << 16), __uint_as_float(ow.y & 0xffff0000u)};
;             gwv[g] = *(const u32x2*)(ZH + rowg * LDZH + 6144 + vb + 8 * g); }
;         __syncthreads();
;         f32x16 acc; for (int i = 0; i < 16; ++i) acc[i] = 0.f;
; #pragma unroll
;         for (int ks = 0; ks < 8; ++ks) { const bf16x8 a = *(const LAS bf16x8*)(STl + (32 * tv + r) * 136 + 16 * ks + 8 * hh), b = *(const LAS bf16x8*)(Q0l + (32 * tt + r) * 136 + 16 * ks + 8 * hh);
;             acc = MFMA32(a, b, acc); }
;         float ss = 0.f;
; #pragma unroll
;         for (int g = 0; g < 4; ++g) {
; #pragma unroll
;             for (int j = 0; j < 4; ++j) { acc[4 * g + j] += oi[g][j]; ss += acc[4 * g + j] * acc[4 * g + j]; } }
;         ss += __shfl_xor(ss, 32);
;         if (hh == 0) SS[t * 4 + tv] = ss;
;         __syncthreads();
;         const float tot = (SS[t * 4] + SS[t * 4 + 1]) + (SS[t * 4 + 2] + SS[t * 4 + 3]);
;         const float rs = 1.f / sqrtf(tot * (1.f / 128.f) + 1e-6f);
.LBB0_850:
	v_lshl_add_u64 v[2:3], v[24:25], 0, v[22:23]
	v_add_co_u32_e32 v4, vcc, 0x24e00000, v2
	s_and_b32 s6, s25, 0x7ffffff0
	s_nop 0
	v_addc_co_u32_e32 v5, vcc, 0, v3, vcc
	v_add_co_u32_e32 v2, vcc, 0x24e04000, v2
	global_load_dwordx4 v[8:11], v[4:5], off
	s_nop 0
	v_addc_co_u32_e32 v3, vcc, 0, v3, vcc
	global_load_dwordx4 v[30:33], v[2:3], off
	v_lshl_add_u64 v[4:5], v[26:27], 0, v[22:23]
	global_load_dwordx4 v[12:15], v[4:5], off
	v_lshl_add_u64 v[2:3], v[28:29], 0, v[22:23]
	global_load_dwordx4 v[34:37], v[2:3], off
	s_and_b32 s10, s3, 0xffffffc0
	s_addk_i32 s6, 0x3000
	s_cmpk_lt_i32 s25, 0x1000
	s_cselect_b32 s17, s10, s6
	s_cselect_b32 s26, 64, 16
	s_and_b32 s16, s20, 0x780
	s_lshl_b32 s6, s16, 1
	v_mov_b32_e32 v2, 0
	v_mov_b32_e32 v3, 0
	v_mov_b32_e32 v4, 0
	v_mov_b32_e32 v5, 0
	v_mov_b32_e32 v38, 0
	v_mov_b32_e32 v39, 0
	v_mov_b32_e32 v40, 0
	v_mov_b32_e32 v41, 0
	v_lshl_add_u64 v[6:7], v[20:21], 0, s[6:7]
	v_cmp_gt_u32_e32 vcc, s26, v56
	s_and_saveexec_b64 s[10:11], vcc
	v_add_u32_e32 v2, s17, v56
	v_ashrrev_i32_e32 v3, 31, v2
	v_lshlrev_b64 v[2:3], 12, v[2:3]
	v_lshl_add_u64 v[2:3], v[6:7], 0, v[2:3]
	global_load_dwordx4 v[2:5], v[2:3], off
	s_or_b64 exec, exec, s[10:11]
	v_cmp_gt_u32_e32 vcc, s26, v57
	s_and_saveexec_b64 s[10:11], vcc
	v_add_u32_e32 v38, s17, v57
	v_ashrrev_i32_e32 v39, 31, v38
	v_lshlrev_b64 v[38:39], 12, v[38:39]
	v_lshl_add_u64 v[38:39], v[6:7], 0, v[38:39]
	global_load_dwordx4 v[38:41], v[38:39], off
	s_or_b64 exec, exec, s[10:11]
	v_cmp_gt_u32_e32 vcc, s26, v1
	s_waitcnt vmcnt(0)
	ds_write_b128 v58, v[8:11]
	ds_write_b128 v59, v[12:15]
	ds_write_b128 v58, v[30:33] offset:17408
	ds_write_b128 v60, v[34:37]
	ds_write_b128 v58, v[2:5] offset:34816
	ds_write_b128 v59, v[38:41] offset:34816
	v_add_u32_e32 v36, s16, v50
	v_cndmask_b32_e32 v2, 0, v1, vcc
	v_add_u32_e32 v2, s17, v2
	v_ashrrev_i32_e32 v3, 31, v2
	v_lshlrev_b64 v[42:43], 12, v[2:3]
	v_readlane_b32 s10, v240, 19
	v_lshlrev_b64 v[2:3], 14, v[2:3]
	v_readlane_b32 s11, v240, 20
	v_lshlrev_b32_e32 v18, 1, v36
	v_lshl_add_u64 v[2:3], s[90:91], 0, v[2:3]
	v_lshl_add_u64 v[4:5], s[10:11], 0, v[42:43]
	v_lshl_add_u64 v[2:3], v[2:3], 0, v[18:19]
	v_lshl_add_u64 v[4:5], v[4:5], 0, v[18:19]
	v_lshl_add_u64 v[6:7], v[2:3], 0, s[14:15]
	v_add_co_u32_e64 v2, s[10:11], s23, v2
	s_nop 1
	v_addc_co_u32_e64 v3, s[10:11], 0, v3, s[10:11]
	global_load_dwordx2 v[72:73], v[4:5], off
	global_load_dwordx2 v[74:75], v[4:5], off offset:16
	global_load_dwordx2 v[76:77], v[4:5], off offset:32
	global_load_dwordx2 v[78:79], v[4:5], off offset:48
	global_load_dwordx2 v[44:45], v[2:3], off
	global_load_dwordx2 v[34:35], v[6:7], off offset:16
	global_load_dwordx2 v[32:33], v[6:7], off offset:32
	global_load_dwordx2 v[30:31], v[6:7], off offset:48
	s_waitcnt lgkmcnt(0)
	s_barrier
	ds_read_b128 v[2:5], v51
	ds_read_b128 v[6:9], v52 offset:34816
	ds_read_b128 v[38:41], v51 offset:32
	ds_read_b128 v[46:49], v52 offset:34848
	s_waitcnt lgkmcnt(2)
	v_mfma_f32_32x32x16_bf16 v[2:17], v[2:5], v[6:9], 0
	s_waitcnt lgkmcnt(0)
	v_mfma_f32_32x32x16_bf16 v[2:17], v[38:41], v[46:49], v[2:17]
	ds_read_b128 v[38:41], v51 offset:64
	ds_read_b128 v[46:49], v52 offset:34880
	ds_read_b128 v[64:67], v51 offset:96
	ds_read_b128 v[68:71], v52 offset:34912
	s_waitcnt lgkmcnt(2)
	v_mfma_f32_32x32x16_bf16 v[2:17], v[38:41], v[46:49], v[2:17]
	s_waitcnt lgkmcnt(0)
	v_mfma_f32_32x32x16_bf16 v[2:17], v[64:67], v[68:71], v[2:17]
	ds_read_b128 v[38:41], v51 offset:128
	ds_read_b128 v[46:49], v52 offset:34944
	ds_read_b128 v[64:67], v51 offset:160
	ds_read_b128 v[68:71], v52 offset:34976
	s_waitcnt lgkmcnt(2)
	v_mfma_f32_32x32x16_bf16 v[2:17], v[38:41], v[46:49], v[2:17]
	s_waitcnt lgkmcnt(0)
	v_mfma_f32_32x32x16_bf16 v[2:17], v[64:67], v[68:71], v[2:17]
	ds_read_b128 v[38:41], v51 offset:192
	ds_read_b128 v[46:49], v52 offset:35008
	ds_read_b128 v[64:67], v51 offset:224
	ds_read_b128 v[68:71], v52 offset:35040
	s_waitcnt lgkmcnt(2)
	v_mfma_f32_32x32x16_bf16 v[2:17], v[38:41], v[46:49], v[2:17]
	s_waitcnt vmcnt(7)
	v_lshlrev_b32_e32 v38, 16, v72
	s_waitcnt lgkmcnt(0)
	v_mfma_f32_32x32x16_bf16 v[2:17], v[64:67], v[68:71], v[2:17]
	v_and_b32_e32 v39, 0xffff0000, v72
	v_lshlrev_b32_e32 v40, 16, v73
	v_and_b32_e32 v41, 0xffff0000, v73
	s_waitcnt vmcnt(6)
	v_lshlrev_b32_e32 v64, 16, v74
	v_and_b32_e32 v65, 0xffff0000, v74
	s_waitcnt vmcnt(5)
	v_lshlrev_b32_e32 v68, 16, v76
	v_and_b32_e32 v69, 0xffff0000, v76
	s_nop 2
	v_pk_add_f32 v[46:47], v[2:3], v[38:39]
	v_lshlrev_b32_e32 v66, 16, v75
	v_and_b32_e32 v67, 0xffff0000, v75
	v_lshlrev_b32_e32 v70, 16, v77
	v_and_b32_e32 v71, 0xffff0000, v77
	v_pk_add_f32 v[48:49], v[4:5], v[40:41]
	v_pk_add_f32 v[38:39], v[6:7], v[64:65]
	v_pk_add_f32 v[6:7], v[10:11], v[68:69]
	v_pk_mul_f32 v[10:11], v[46:47], v[46:47]
	v_pk_add_f32 v[40:41], v[8:9], v[66:67]
	v_pk_add_f32 v[8:9], v[12:13], v[70:71]
	v_pk_mul_f32 v[12:13], v[48:49], v[48:49]
	v_add_f32_e32 v10, v10, v11
	s_waitcnt vmcnt(4)
	v_lshlrev_b32_e32 v72, 16, v78
	v_and_b32_e32 v73, 0xffff0000, v78
	v_add_f32_e32 v10, v12, v10
	v_pk_add_f32 v[2:3], v[14:15], v[72:73]
	v_pk_mul_f32 v[14:15], v[38:39], v[38:39]
	v_add_f32_e32 v10, v13, v10
	v_lshlrev_b32_e32 v74, 16, v79
	v_and_b32_e32 v75, 0xffff0000, v79
	v_add_f32_e32 v10, v14, v10
	v_pk_add_f32 v[4:5], v[16:17], v[74:75]
	v_pk_mul_f32 v[16:17], v[40:41], v[40:41]
	v_add_f32_e32 v10, v15, v10
	v_add_f32_e32 v10, v16, v10
	v_pk_mul_f32 v[64:65], v[6:7], v[6:7]
	v_add_f32_e32 v10, v17, v10
	v_add_f32_e32 v10, v64, v10
	v_pk_mul_f32 v[66:67], v[8:9], v[8:9]
	v_add_f32_e32 v10, v65, v10
	v_add_f32_e32 v10, v66, v10
	v_pk_mul_f32 v[68:69], v[2:3], v[2:3]
	v_add_f32_e32 v10, v67, v10
	v_add_f32_e32 v10, v68, v10
	v_pk_mul_f32 v[70:71], v[4:5], v[4:5]
	v_add_f32_e32 v10, v69, v10
	v_add_f32_e32 v10, v70, v10
	v_add_f32_e32 v10, v71, v10
	ds_bpermute_b32 v11, v53, v10
	s_and_saveexec_b64 s[10:11], s[8:9]
	s_cbranch_execz .LBB0_856
	s_waitcnt lgkmcnt(0)
	v_add_f32_e32 v10, v10, v11
	ds_write_b32 v55, v10 offset:52224
